# P4 mid-K gate-rescale hook: all gate loads issued at the hook head into dead fragment registers; the four vmcnt(0) drains become counted waits + register moves
# speedup vs baseline: 1.0017x; 1.0017x over previous
;     __device__ __forceinline__ void mid(f32x4 (&acc)[2][2][4][2], const Unit& u, int wr, int wc, int fr, int fq) const {
;         const int col0 = u.pn * 256 + wc * 32 + 8 * fq;
;         u32x2 ac[2], bc[2], an[2], bn[2];
; #pragma unroll
;         for (int bj = 0; bj < 2; ++bj) { const unsigned char* p = gates + (size_t)ROW_OF(0, 0) * (2 * D) + col0 + bj * 128; ac[bj] = *(const u32x2*)p; bc[bj] = *(const u32x2*)(p + D); }
; #pragma unroll
;         for (int g = 0; g < 8; ++g) {
;             const int ai = g >> 2, m = g & 3;
;             if (g < 7) {
; #pragma unroll
;                 for (int bj = 0; bj < 2; ++bj) { const unsigned char* p = gates + (size_t)ROW_OF((g + 1) >> 2, (g + 1) & 3) * (2 * D) + col0 + bj * 128; an[bj] = *(const u32x2*)p; bn[bj] = *(const u32x2*)(p + D); }
;             }
; #pragma unroll
;             for (int bj = 0; bj < 2; ++bj) {
;                 const unsigned a0 = ac[bj].x, a1 = ac[bj].y, b0 = bc[bj].x, b1 = bc[bj].y;
;                 f32x4 r0, r1;
; #pragma unroll
;                 for (int j = 0; j < 4; ++j) {
;                     r0[j] = (float)((a0 >> (8 * j)) & 0xff) * __builtin_amdgcn_rcpf(fmaxf((float)((b0 >> (8 * j)) & 0xff), 0.5f));
;                     r1[j] = (float)((a1 >> (8 * j)) & 0xff) * __builtin_amdgcn_rcpf(fmaxf((float)((b1 >> (8 * j)) & 0xff), 0.5f));
;                 }
;                 acc[ai][bj][m][0] = acc[ai][bj][m][0] * r0; acc[ai][bj][m][1] = acc[ai][bj][m][1] * r1;
;             }
;             if (g < 7) { ac[0] = an[0]; ac[1] = an[1]; bc[0] = bn[0]; bc[1] = bn[1]; }
;         }
.LBB0_753:
	s_cmpk_lg_i32 s62, 0x800
	s_cbranch_scc1 .LBB0_752
	v_mov_b32_e32 v1, v165
	v_mov_b32_e32 v3, v164
	s_nop 0
	v_lshl_add_u32 v2, v1, 3, s31
	v_add_u32_e32 v1, s21, v3
	v_add_u32_e32 v152, s34, v1
	v_ashrrev_i32_e32 v153, 31, v152
	v_lshlrev_b64 v[152:153], 12, v[152:153]
	v_lshl_add_u64 v[152:153], s[46:47], 0, v[152:153]
	v_ashrrev_i32_e32 v3, 31, v2
	v_lshl_add_u64 v[152:153], v[152:153], 0, v[2:3]
	global_load_dwordx2 v[162:163], v[152:153], off
	global_load_dwordx2 v[168:169], v[152:153], off offset:2048
	global_load_dwordx2 v[160:161], v[152:153], off offset:128
	global_load_dwordx2 v[170:171], v[152:153], off offset:2176
	v_add_u32_e32 v152, s35, v1
	v_ashrrev_i32_e32 v153, 31, v152
	v_lshlrev_b64 v[152:153], 12, v[152:153]
	v_lshl_add_u64 v[152:153], s[46:47], 0, v[152:153]
	v_lshl_add_u64 v[154:155], v[152:153], 0, v[2:3]
	global_load_dwordx2 v[156:157], v[154:155], off
	global_load_dwordx2 v[158:159], v[154:155], off offset:2048
	global_load_dwordx2 v[152:153], v[154:155], off offset:128
	s_nop 0
	global_load_dwordx2 v[154:155], v[154:155], off offset:2176
	v_add_u32_e32 v246, s45, v1
	v_ashrrev_i32_e32 v247, 31, v246
	v_lshlrev_b64 v[246:247], 12, v[246:247]
	v_lshl_add_u64 v[246:247], s[46:47], 0, v[246:247]
	v_lshl_add_u64 v[246:247], v[246:247], 0, v[2:3]
	global_load_dwordx2 v[184:185], v[246:247], off
	global_load_dwordx2 v[186:187], v[246:247], off offset:2048
	global_load_dwordx2 v[188:189], v[246:247], off offset:128
	global_load_dwordx2 v[190:191], v[246:247], off offset:2176
	v_add_u32_e32 v246, s48, v1
	v_ashrrev_i32_e32 v247, 31, v246
	v_lshlrev_b64 v[246:247], 12, v[246:247]
	v_lshl_add_u64 v[246:247], s[46:47], 0, v[246:247]
	v_lshl_add_u64 v[246:247], v[246:247], 0, v[2:3]
	global_load_dwordx2 v[192:193], v[246:247], off
	global_load_dwordx2 v[194:195], v[246:247], off offset:2048
	global_load_dwordx2 v[196:197], v[246:247], off offset:128
	global_load_dwordx2 v[198:199], v[246:247], off offset:2176
	v_add_u32_e32 v246, s49, v1
	v_ashrrev_i32_e32 v247, 31, v246
	v_lshlrev_b64 v[246:247], 12, v[246:247]
	v_lshl_add_u64 v[246:247], s[46:47], 0, v[246:247]
	v_lshl_add_u64 v[246:247], v[246:247], 0, v[2:3]
	global_load_dwordx2 v[200:201], v[246:247], off
	global_load_dwordx2 v[202:203], v[246:247], off offset:2048
	global_load_dwordx2 v[204:205], v[246:247], off offset:128
	global_load_dwordx2 v[206:207], v[246:247], off offset:2176
	v_add_u32_e32 v246, s57, v1
	v_ashrrev_i32_e32 v247, 31, v246
	v_lshlrev_b64 v[246:247], 12, v[246:247]
	v_lshl_add_u64 v[246:247], s[46:47], 0, v[246:247]
	v_lshl_add_u64 v[246:247], v[246:247], 0, v[2:3]
	global_load_dwordx2 v[208:209], v[246:247], off
	global_load_dwordx2 v[210:211], v[246:247], off offset:2048
	global_load_dwordx2 v[216:217], v[246:247], off offset:128
	global_load_dwordx2 v[218:219], v[246:247], off offset:2176
	v_add_u32_e32 v246, s70, v1
	v_ashrrev_i32_e32 v247, 31, v246
	v_lshlrev_b64 v[246:247], 12, v[246:247]
	v_lshl_add_u64 v[246:247], s[46:47], 0, v[246:247]
	v_lshl_add_u64 v[246:247], v[246:247], 0, v[2:3]
	global_load_dwordx2 v[220:221], v[246:247], off
	global_load_dwordx2 v[222:223], v[246:247], off offset:2048
	global_load_dwordx2 v[224:225], v[246:247], off offset:128
	global_load_dwordx2 v[226:227], v[246:247], off offset:2176
	v_add_u32_e32 v246, s71, v1
	v_ashrrev_i32_e32 v247, 31, v246
	v_lshlrev_b64 v[246:247], 12, v[246:247]
	v_lshl_add_u64 v[246:247], s[46:47], 0, v[246:247]
	v_lshl_add_u64 v[246:247], v[246:247], 0, v[2:3]
	global_load_dwordx2 v[228:229], v[246:247], off
	global_load_dwordx2 v[230:231], v[246:247], off offset:2048
	global_load_dwordx2 v[232:233], v[246:247], off offset:128
	global_load_dwordx2 v[234:235], v[246:247], off offset:2176
	s_waitcnt vmcnt(24)
	v_cvt_f32_ubyte3_e32 v181, v162
	v_cvt_f32_ubyte0_e32 v173, v169
	v_max_f32_e32 v173, 0.5, v173
	v_cvt_f32_ubyte0_e32 v172, v168
	v_rcp_f32_e32 v174, v173
	v_cvt_f32_ubyte1_e32 v173, v168
	v_cvt_f32_ubyte2_e32 v176, v168
	v_cvt_f32_ubyte2_e32 v177, v169
	v_cvt_f32_ubyte3_e32 v168, v168
	v_cvt_f32_ubyte1_e32 v175, v169
	v_max_f32_e32 v176, 0.5, v176
	v_max_f32_e32 v177, 0.5, v177
	v_max_f32_e32 v168, 0.5, v168
	v_max_f32_e32 v175, 0.5, v175
	v_rcp_f32_e32 v176, v176
	v_rcp_f32_e32 v178, v177
	v_rcp_f32_e32 v177, v168
	v_rcp_f32_e32 v175, v175
	v_cvt_f32_ubyte2_e32 v180, v162
	v_cvt_f32_ubyte1_e32 v183, v162
	v_cvt_f32_ubyte0_e32 v182, v162
	v_cvt_f32_ubyte3_e32 v162, v169
	v_max_f32_e32 v172, 0.5, v172
	v_max_f32_e32 v173, 0.5, v173
	v_max_f32_e32 v162, 0.5, v162
	v_rcp_f32_e32 v172, v172
	v_rcp_f32_e32 v173, v173
	v_rcp_f32_e32 v179, v162
	v_pk_mul_f32 v[176:177], v[176:177], v[180:181]
	v_cvt_f32_ubyte1_e32 v181, v163
	v_cvt_f32_ubyte0_e32 v180, v163
	v_cvt_f32_ubyte3_e32 v169, v163
	v_cvt_f32_ubyte2_e32 v168, v163
	v_pk_mul_f32 v[162:163], v[174:175], v[180:181]
	v_pk_mul_f32 v[172:173], v[172:173], v[182:183]
	v_pk_mul_f32 v[124:125], v[124:125], v[162:163]
	v_cvt_f32_ubyte0_e32 v163, v171
	v_pk_mul_f32 v[168:169], v[178:179], v[168:169]
	v_max_f32_e32 v163, 0.5, v163
	v_pk_mul_f32 v[128:129], v[128:129], v[172:173]
	v_pk_mul_f32 v[126:127], v[126:127], v[168:169]
	v_cvt_f32_ubyte0_e32 v162, v170
	v_rcp_f32_e32 v168, v163
	v_cvt_f32_ubyte1_e32 v163, v170
	v_cvt_f32_ubyte2_e32 v172, v170
	v_cvt_f32_ubyte2_e32 v173, v171
	v_cvt_f32_ubyte3_e32 v170, v170
	v_cvt_f32_ubyte1_e32 v169, v171
	v_max_f32_e32 v172, 0.5, v172
	v_max_f32_e32 v173, 0.5, v173
	v_max_f32_e32 v170, 0.5, v170
	v_max_f32_e32 v169, 0.5, v169
	v_rcp_f32_e32 v172, v172
	v_rcp_f32_e32 v174, v173
	v_rcp_f32_e32 v173, v170
	v_rcp_f32_e32 v169, v169
	v_pk_mul_f32 v[130:131], v[130:131], v[176:177]
;     __device__ __forceinline__ void mid(f32x4 (&acc)[2][2][4][2], const Unit& u, int wr, int wc, int fr, int fq) const {
;     ...
;         for (int g = 0; g < 8; ++g) {
;             const int ai = g >> 2, m = g & 3;
;             if (g < 7) {
; #pragma unroll
;                 for (int bj = 0; bj < 2; ++bj) { const unsigned char* p = gates + (size_t)ROW_OF((g + 1) >> 2, (g + 1) & 3) * (2 * D) + col0 + bj * 128; an[bj] = *(const u32x2*)p; bn[bj] = *(const u32x2*)(p + D); }
;             }
; #pragma unroll
;             for (int bj = 0; bj < 2; ++bj) {
;                 const unsigned a0 = ac[bj].x, a1 = ac[bj].y, b0 = bc[bj].x, b1 = bc[bj].y;
;                 f32x4 r0, r1;
; #pragma unroll
;                 for (int j = 0; j < 4; ++j) {
;                     r0[j] = (float)((a0 >> (8 * j)) & 0xff) * __builtin_amdgcn_rcpf(fmaxf((float)((b0 >> (8 * j)) & 0xff), 0.5f));
;                     r1[j] = (float)((a1 >> (8 * j)) & 0xff) * __builtin_amdgcn_rcpf(fmaxf((float)((b1 >> (8 * j)) & 0xff), 0.5f));
;                 }
;                 acc[ai][bj][m][0] = acc[ai][bj][m][0] * r0; acc[ai][bj][m][1] = acc[ai][bj][m][1] * r1;
;             }
;             if (g < 7) { ac[0] = an[0]; ac[1] = an[1]; bc[0] = bn[0]; bc[1] = bn[1]; }
	v_cvt_f32_ubyte3_e32 v177, v160
	v_cvt_f32_ubyte2_e32 v176, v160
	v_cvt_f32_ubyte1_e32 v179, v160
	v_cvt_f32_ubyte0_e32 v178, v160
	v_cvt_f32_ubyte3_e32 v160, v171
	v_max_f32_e32 v162, 0.5, v162
	v_max_f32_e32 v163, 0.5, v163
	v_pk_mul_f32 v[172:173], v[172:173], v[176:177]
	v_max_f32_e32 v160, 0.5, v160
	v_cvt_f32_ubyte1_e32 v177, v161
	v_cvt_f32_ubyte0_e32 v176, v161
	v_rcp_f32_e32 v162, v162
	v_rcp_f32_e32 v163, v163
	v_rcp_f32_e32 v175, v160
	v_cvt_f32_ubyte3_e32 v171, v161
	v_cvt_f32_ubyte2_e32 v170, v161
	v_pk_mul_f32 v[160:161], v[168:169], v[176:177]
	v_pk_mul_f32 v[162:163], v[162:163], v[178:179]
	v_pk_mul_f32 v[116:117], v[116:117], v[160:161]
	v_add_u32_e32 v160, s45, v1
	v_ashrrev_i32_e32 v161, 31, v160
	v_lshlrev_b64 v[160:161], 12, v[160:161]
	v_lshl_add_u64 v[160:161], s[46:47], 0, v[160:161]
	v_pk_mul_f32 v[168:169], v[174:175], v[170:171]
	v_pk_mul_f32 v[120:121], v[120:121], v[162:163]
	v_lshl_add_u64 v[162:163], v[160:161], 0, v[2:3]
	v_pk_mul_f32 v[118:119], v[118:119], v[168:169]
	s_nop 0
	v_pk_mul_f32 v[122:123], v[122:123], v[172:173]
	v_cvt_f32_ubyte0_e32 v173, v159
	v_max_f32_e32 v173, 0.5, v173
	v_cvt_f32_ubyte0_e32 v172, v158
	v_rcp_f32_e32 v174, v173
	v_cvt_f32_ubyte1_e32 v173, v158
	v_cvt_f32_ubyte2_e32 v176, v158
	v_cvt_f32_ubyte2_e32 v177, v159
	v_cvt_f32_ubyte3_e32 v158, v158
	v_cvt_f32_ubyte1_e32 v175, v159
	v_max_f32_e32 v176, 0.5, v176
	v_max_f32_e32 v177, 0.5, v177
	v_max_f32_e32 v158, 0.5, v158
	v_max_f32_e32 v175, 0.5, v175
	v_rcp_f32_e32 v176, v176
	v_rcp_f32_e32 v178, v177
	v_rcp_f32_e32 v177, v158
	v_rcp_f32_e32 v175, v175
	v_cvt_f32_ubyte3_e32 v181, v156
	v_cvt_f32_ubyte2_e32 v180, v156
	v_cvt_f32_ubyte1_e32 v183, v156
	v_cvt_f32_ubyte0_e32 v182, v156
	v_cvt_f32_ubyte3_e32 v156, v159
	v_max_f32_e32 v172, 0.5, v172
	v_max_f32_e32 v173, 0.5, v173
	v_max_f32_e32 v156, 0.5, v156
	v_rcp_f32_e32 v172, v172
	v_rcp_f32_e32 v173, v173
	v_rcp_f32_e32 v179, v156
	v_pk_mul_f32 v[176:177], v[176:177], v[180:181]
	v_cvt_f32_ubyte1_e32 v181, v157
	v_cvt_f32_ubyte0_e32 v180, v157
	v_cvt_f32_ubyte3_e32 v159, v157
	v_cvt_f32_ubyte2_e32 v158, v157
	v_pk_mul_f32 v[156:157], v[174:175], v[180:181]
	v_pk_mul_f32 v[172:173], v[172:173], v[182:183]
	v_pk_mul_f32 v[108:109], v[108:109], v[156:157]
	v_cvt_f32_ubyte0_e32 v157, v155
	v_pk_mul_f32 v[158:159], v[178:179], v[158:159]
	v_max_f32_e32 v157, 0.5, v157
	v_pk_mul_f32 v[112:113], v[112:113], v[172:173]
	v_pk_mul_f32 v[110:111], v[110:111], v[158:159]
	v_cvt_f32_ubyte0_e32 v156, v154
	v_rcp_f32_e32 v158, v157
	v_cvt_f32_ubyte1_e32 v157, v154
	v_cvt_f32_ubyte2_e32 v172, v154
	v_cvt_f32_ubyte2_e32 v173, v155
	v_cvt_f32_ubyte3_e32 v154, v154
	v_cvt_f32_ubyte1_e32 v159, v155
	v_max_f32_e32 v172, 0.5, v172
	v_max_f32_e32 v173, 0.5, v173
	v_max_f32_e32 v154, 0.5, v154
	v_max_f32_e32 v159, 0.5, v159
	v_rcp_f32_e32 v172, v172
	v_rcp_f32_e32 v174, v173
	v_rcp_f32_e32 v173, v154
	v_rcp_f32_e32 v159, v159
	v_pk_mul_f32 v[114:115], v[114:115], v[176:177]
	v_cvt_f32_ubyte3_e32 v177, v152
	v_cvt_f32_ubyte2_e32 v176, v152
	v_cvt_f32_ubyte1_e32 v179, v152
	v_cvt_f32_ubyte0_e32 v178, v152
	v_cvt_f32_ubyte3_e32 v152, v155
	v_pk_mul_f32 v[172:173], v[172:173], v[176:177]
	v_max_f32_e32 v152, 0.5, v152
	v_cvt_f32_ubyte1_e32 v177, v153
	v_cvt_f32_ubyte0_e32 v176, v153
	v_max_f32_e32 v156, 0.5, v156
	v_max_f32_e32 v157, 0.5, v157
	v_rcp_f32_e32 v175, v152
	v_cvt_f32_ubyte3_e32 v155, v153
	v_cvt_f32_ubyte2_e32 v154, v153
	v_pk_mul_f32 v[152:153], v[158:159], v[176:177]
	v_rcp_f32_e32 v156, v156
	v_rcp_f32_e32 v157, v157
	v_pk_mul_f32 v[100:101], v[100:101], v[152:153]
	v_add_u32_e32 v152, s48, v1
	v_ashrrev_i32_e32 v153, 31, v152
	v_lshlrev_b64 v[152:153], 12, v[152:153]
	v_pk_mul_f32 v[154:155], v[174:175], v[154:155]
	v_lshl_add_u64 v[152:153], s[46:47], 0, v[152:153]
	v_pk_mul_f32 v[156:157], v[156:157], v[178:179]
	v_pk_mul_f32 v[102:103], v[102:103], v[154:155]
	v_lshl_add_u64 v[154:155], v[152:153], 0, v[2:3]
	v_pk_mul_f32 v[106:107], v[106:107], v[172:173]
	v_pk_mul_f32 v[104:105], v[104:105], v[156:157]
	s_waitcnt vmcnt(16)
	v_mov_b64_e32 v[168:169], v[184:185]
	v_mov_b64_e32 v[170:171], v[186:187]
	v_mov_b64_e32 v[160:161], v[188:189]
	v_mov_b64_e32 v[162:163], v[190:191]
	v_mov_b64_e32 v[172:173], v[192:193]
	v_mov_b64_e32 v[174:175], v[194:195]
	v_mov_b64_e32 v[152:153], v[196:197]
	v_mov_b64_e32 v[156:157], v[198:199]
	v_cvt_f32_ubyte0_e32 v155, v171
	v_max_f32_e32 v155, 0.5, v155
	v_cvt_f32_ubyte0_e32 v154, v170
	v_rcp_f32_e32 v158, v155
	v_cvt_f32_ubyte1_e32 v155, v170
	v_max_f32_e32 v154, 0.5, v154
	v_max_f32_e32 v155, 0.5, v155
	v_cvt_f32_ubyte2_e32 v176, v170
	v_cvt_f32_ubyte2_e32 v177, v171
	v_cvt_f32_ubyte3_e32 v170, v170
	v_rcp_f32_e32 v154, v154
	v_rcp_f32_e32 v155, v155
	v_cvt_f32_ubyte1_e32 v159, v171
	v_max_f32_e32 v176, 0.5, v176
	v_max_f32_e32 v177, 0.5, v177
	v_max_f32_e32 v170, 0.5, v170
	v_max_f32_e32 v159, 0.5, v159
	v_rcp_f32_e32 v176, v176
	v_rcp_f32_e32 v178, v177
	v_rcp_f32_e32 v177, v170
	v_rcp_f32_e32 v159, v159
	v_cvt_f32_ubyte3_e32 v181, v168
	v_cvt_f32_ubyte2_e32 v180, v168
	v_cvt_f32_ubyte1_e32 v183, v168
	v_cvt_f32_ubyte0_e32 v182, v168
	v_cvt_f32_ubyte3_e32 v168, v171
	v_pk_mul_f32 v[154:155], v[154:155], v[182:183]
	v_max_f32_e32 v168, 0.5, v168
	v_pk_mul_f32 v[176:177], v[176:177], v[180:181]
	v_rcp_f32_e32 v179, v168
	v_cvt_f32_ubyte1_e32 v181, v169
	v_cvt_f32_ubyte0_e32 v180, v169
	v_pk_mul_f32 v[96:97], v[96:97], v[154:155]
	v_cvt_f32_ubyte0_e32 v155, v163
	v_pk_mul_f32 v[158:159], v[158:159], v[180:181]
	v_max_f32_e32 v155, 0.5, v155
	v_pk_mul_f32 v[92:93], v[92:93], v[158:159]
	v_cvt_f32_ubyte0_e32 v154, v162
	v_rcp_f32_e32 v158, v155
;     __device__ __forceinline__ void mid(f32x4 (&acc)[2][2][4][2], const Unit& u, int wr, int wc, int fr, int fq) const {
;     ...
;         for (int g = 0; g < 8; ++g) {
;             const int ai = g >> 2, m = g & 3;
;             if (g < 7) {
; #pragma unroll
;                 for (int bj = 0; bj < 2; ++bj) { const unsigned char* p = gates + (size_t)ROW_OF((g + 1) >> 2, (g + 1) & 3) * (2 * D) + col0 + bj * 128; an[bj] = *(const u32x2*)p; bn[bj] = *(const u32x2*)(p + D); }
;             }
; #pragma unroll
;             for (int bj = 0; bj < 2; ++bj) {
;                 const unsigned a0 = ac[bj].x, a1 = ac[bj].y, b0 = bc[bj].x, b1 = bc[bj].y;
;                 f32x4 r0, r1;
; #pragma unroll
;                 for (int j = 0; j < 4; ++j) {
;                     r0[j] = (float)((a0 >> (8 * j)) & 0xff) * __builtin_amdgcn_rcpf(fmaxf((float)((b0 >> (8 * j)) & 0xff), 0.5f));
;                     r1[j] = (float)((a1 >> (8 * j)) & 0xff) * __builtin_amdgcn_rcpf(fmaxf((float)((b1 >> (8 * j)) & 0xff), 0.5f));
;                 }
;                 acc[ai][bj][m][0] = acc[ai][bj][m][0] * r0; acc[ai][bj][m][1] = acc[ai][bj][m][1] * r1;
;             }
;             if (g < 7) { ac[0] = an[0]; ac[1] = an[1]; bc[0] = bn[0]; bc[1] = bn[1]; }
	v_cvt_f32_ubyte1_e32 v155, v162
	v_cvt_f32_ubyte3_e32 v171, v169
	v_cvt_f32_ubyte2_e32 v170, v169
	v_max_f32_e32 v154, 0.5, v154
	v_max_f32_e32 v155, 0.5, v155
	v_pk_mul_f32 v[168:169], v[178:179], v[170:171]
	v_rcp_f32_e32 v154, v154
	v_rcp_f32_e32 v155, v155
	v_pk_mul_f32 v[94:95], v[94:95], v[168:169]
	v_cvt_f32_ubyte2_e32 v168, v162
	v_cvt_f32_ubyte2_e32 v169, v163
	v_cvt_f32_ubyte3_e32 v162, v162
	v_cvt_f32_ubyte1_e32 v159, v163
	v_max_f32_e32 v168, 0.5, v168
	v_max_f32_e32 v169, 0.5, v169
	v_max_f32_e32 v162, 0.5, v162
	v_pk_mul_f32 v[98:99], v[98:99], v[176:177]
	v_max_f32_e32 v159, 0.5, v159
	v_rcp_f32_e32 v168, v168
	v_rcp_f32_e32 v170, v169
	v_rcp_f32_e32 v169, v162
	v_cvt_f32_ubyte3_e32 v177, v160
	v_cvt_f32_ubyte2_e32 v176, v160
	v_cvt_f32_ubyte1_e32 v179, v160
	v_cvt_f32_ubyte0_e32 v178, v160
	v_cvt_f32_ubyte3_e32 v160, v163
	v_rcp_f32_e32 v159, v159
	v_pk_mul_f32 v[154:155], v[154:155], v[178:179]
	v_max_f32_e32 v160, 0.5, v160
	v_rcp_f32_e32 v171, v160
	v_pk_mul_f32 v[88:89], v[88:89], v[154:155]
	v_add_u32_e32 v154, s49, v1
	v_ashrrev_i32_e32 v155, 31, v154
	v_pk_mul_f32 v[168:169], v[168:169], v[176:177]
	v_cvt_f32_ubyte1_e32 v177, v161
	v_cvt_f32_ubyte0_e32 v176, v161
	v_lshlrev_b64 v[154:155], 12, v[154:155]
	v_cvt_f32_ubyte3_e32 v163, v161
	v_cvt_f32_ubyte2_e32 v162, v161
	v_pk_mul_f32 v[158:159], v[158:159], v[176:177]
	v_lshl_add_u64 v[154:155], s[46:47], 0, v[154:155]
	v_pk_mul_f32 v[160:161], v[170:171], v[162:163]
	v_pk_mul_f32 v[84:85], v[84:85], v[158:159]
	v_lshl_add_u64 v[158:159], v[154:155], 0, v[2:3]
	v_pk_mul_f32 v[86:87], v[86:87], v[160:161]
	s_nop 0
	v_pk_mul_f32 v[90:91], v[90:91], v[168:169]
	v_cvt_f32_ubyte0_e32 v169, v175
	v_max_f32_e32 v169, 0.5, v169
	v_cvt_f32_ubyte0_e32 v168, v174
	v_rcp_f32_e32 v170, v169
	v_cvt_f32_ubyte1_e32 v169, v174
	v_max_f32_e32 v168, 0.5, v168
	v_max_f32_e32 v169, 0.5, v169
	v_cvt_f32_ubyte2_e32 v176, v174
	v_cvt_f32_ubyte2_e32 v177, v175
	v_cvt_f32_ubyte3_e32 v174, v174
	v_rcp_f32_e32 v168, v168
	v_rcp_f32_e32 v169, v169
	v_cvt_f32_ubyte1_e32 v171, v175
	v_max_f32_e32 v176, 0.5, v176
	v_max_f32_e32 v177, 0.5, v177
	v_max_f32_e32 v174, 0.5, v174
	v_cvt_f32_ubyte3_e32 v181, v172
	v_cvt_f32_ubyte2_e32 v180, v172
	v_cvt_f32_ubyte1_e32 v183, v172
	v_cvt_f32_ubyte0_e32 v182, v172
	v_cvt_f32_ubyte3_e32 v172, v175
	v_max_f32_e32 v171, 0.5, v171
	v_rcp_f32_e32 v176, v176
	v_rcp_f32_e32 v178, v177
	v_rcp_f32_e32 v177, v174
	v_max_f32_e32 v172, 0.5, v172
	v_rcp_f32_e32 v171, v171
	v_rcp_f32_e32 v179, v172
	v_pk_mul_f32 v[168:169], v[168:169], v[182:183]
	v_pk_mul_f32 v[176:177], v[176:177], v[180:181]
	v_cvt_f32_ubyte3_e32 v175, v173
	v_cvt_f32_ubyte2_e32 v174, v173
	v_cvt_f32_ubyte1_e32 v181, v173
	v_cvt_f32_ubyte0_e32 v180, v173
	v_pk_mul_f32 v[80:81], v[80:81], v[168:169]
	v_cvt_f32_ubyte0_e32 v169, v157
	v_pk_mul_f32 v[170:171], v[170:171], v[180:181]
	v_pk_mul_f32 v[172:173], v[178:179], v[174:175]
	v_max_f32_e32 v169, 0.5, v169
	v_pk_mul_f32 v[78:79], v[78:79], v[172:173]
	v_pk_mul_f32 v[76:77], v[76:77], v[170:171]
	v_cvt_f32_ubyte0_e32 v168, v156
	v_rcp_f32_e32 v170, v169
	v_cvt_f32_ubyte1_e32 v169, v156
	v_cvt_f32_ubyte2_e32 v172, v156
	v_cvt_f32_ubyte2_e32 v173, v157
	v_cvt_f32_ubyte3_e32 v156, v156
	v_cvt_f32_ubyte1_e32 v171, v157
	v_max_f32_e32 v172, 0.5, v172
	v_max_f32_e32 v173, 0.5, v173
	v_max_f32_e32 v156, 0.5, v156
	v_max_f32_e32 v171, 0.5, v171
	v_rcp_f32_e32 v172, v172
	v_rcp_f32_e32 v174, v173
	v_rcp_f32_e32 v173, v156
	v_rcp_f32_e32 v171, v171
	v_pk_mul_f32 v[82:83], v[82:83], v[176:177]
	v_cvt_f32_ubyte3_e32 v177, v152
	v_cvt_f32_ubyte2_e32 v176, v152
	v_cvt_f32_ubyte1_e32 v179, v152
	v_cvt_f32_ubyte0_e32 v178, v152
	v_cvt_f32_ubyte3_e32 v152, v157
	v_pk_mul_f32 v[172:173], v[172:173], v[176:177]
	v_max_f32_e32 v152, 0.5, v152
	v_cvt_f32_ubyte1_e32 v177, v153
	v_cvt_f32_ubyte0_e32 v176, v153
	v_max_f32_e32 v168, 0.5, v168
	v_max_f32_e32 v169, 0.5, v169
	v_rcp_f32_e32 v175, v152
	v_cvt_f32_ubyte3_e32 v157, v153
	v_cvt_f32_ubyte2_e32 v156, v153
	v_pk_mul_f32 v[152:153], v[170:171], v[176:177]
	v_rcp_f32_e32 v168, v168
	v_rcp_f32_e32 v169, v169
	v_pk_mul_f32 v[68:69], v[68:69], v[152:153]
	v_add_u32_e32 v152, s57, v1
	v_ashrrev_i32_e32 v153, 31, v152
	v_lshlrev_b64 v[152:153], 12, v[152:153]
	v_pk_mul_f32 v[156:157], v[174:175], v[156:157]
	v_lshl_add_u64 v[152:153], s[46:47], 0, v[152:153]
	v_pk_mul_f32 v[168:169], v[168:169], v[178:179]
	v_pk_mul_f32 v[70:71], v[70:71], v[156:157]
	v_lshl_add_u64 v[156:157], v[152:153], 0, v[2:3]
	v_pk_mul_f32 v[72:73], v[72:73], v[168:169]
	s_nop 0
	v_pk_mul_f32 v[74:75], v[74:75], v[172:173]
	s_waitcnt vmcnt(8)
;     __device__ __forceinline__ void mid(f32x4 (&acc)[2][2][4][2], const Unit& u, int wr, int wc, int fr, int fq) const {
;     ...
;         for (int g = 0; g < 8; ++g) {
;             const int ai = g >> 2, m = g & 3;
;             if (g < 7) {
; #pragma unroll
;                 for (int bj = 0; bj < 2; ++bj) { const unsigned char* p = gates + (size_t)ROW_OF((g + 1) >> 2, (g + 1) & 3) * (2 * D) + col0 + bj * 128; an[bj] = *(const u32x2*)p; bn[bj] = *(const u32x2*)(p + D); }
;             }
; #pragma unroll
;             for (int bj = 0; bj < 2; ++bj) {
;                 const unsigned a0 = ac[bj].x, a1 = ac[bj].y, b0 = bc[bj].x, b1 = bc[bj].y;
;                 f32x4 r0, r1;
; #pragma unroll
;                 for (int j = 0; j < 4; ++j) {
;                     r0[j] = (float)((a0 >> (8 * j)) & 0xff) * __builtin_amdgcn_rcpf(fmaxf((float)((b0 >> (8 * j)) & 0xff), 0.5f));
;                     r1[j] = (float)((a1 >> (8 * j)) & 0xff) * __builtin_amdgcn_rcpf(fmaxf((float)((b1 >> (8 * j)) & 0xff), 0.5f));
;                 }
;                 acc[ai][bj][m][0] = acc[ai][bj][m][0] * r0; acc[ai][bj][m][1] = acc[ai][bj][m][1] * r1;
;             }
;             if (g < 7) { ac[0] = an[0]; ac[1] = an[1]; bc[0] = bn[0]; bc[1] = bn[1]; }
	v_mov_b64_e32 v[160:161], v[200:201]
	v_mov_b64_e32 v[162:163], v[202:203]
	v_mov_b64_e32 v[154:155], v[204:205]
	v_mov_b64_e32 v[158:159], v[206:207]
	v_mov_b64_e32 v[168:169], v[208:209]
	v_mov_b64_e32 v[170:171], v[210:211]
	v_mov_b64_e32 v[152:153], v[216:217]
	v_mov_b64_e32 v[156:157], v[218:219]
	v_cvt_f32_ubyte0_e32 v173, v163
	v_max_f32_e32 v173, 0.5, v173
	v_cvt_f32_ubyte0_e32 v172, v162
	v_rcp_f32_e32 v174, v173
	v_cvt_f32_ubyte1_e32 v173, v162
	v_cvt_f32_ubyte2_e32 v176, v162
	v_cvt_f32_ubyte2_e32 v177, v163
	v_cvt_f32_ubyte3_e32 v162, v162
	v_cvt_f32_ubyte1_e32 v175, v163
	v_max_f32_e32 v176, 0.5, v176
	v_max_f32_e32 v177, 0.5, v177
	v_max_f32_e32 v162, 0.5, v162
	v_max_f32_e32 v175, 0.5, v175
	v_rcp_f32_e32 v176, v176
	v_rcp_f32_e32 v178, v177
	v_rcp_f32_e32 v177, v162
	v_rcp_f32_e32 v175, v175
	v_cvt_f32_ubyte3_e32 v181, v160
	v_cvt_f32_ubyte2_e32 v180, v160
	v_cvt_f32_ubyte1_e32 v183, v160
	v_cvt_f32_ubyte0_e32 v182, v160
	v_cvt_f32_ubyte3_e32 v160, v163
	v_max_f32_e32 v172, 0.5, v172
	v_max_f32_e32 v173, 0.5, v173
	v_max_f32_e32 v160, 0.5, v160
	v_rcp_f32_e32 v172, v172
	v_rcp_f32_e32 v173, v173
	v_rcp_f32_e32 v179, v160
	v_pk_mul_f32 v[176:177], v[176:177], v[180:181]
	v_cvt_f32_ubyte1_e32 v181, v161
	v_cvt_f32_ubyte0_e32 v180, v161
	v_cvt_f32_ubyte3_e32 v163, v161
	v_cvt_f32_ubyte2_e32 v162, v161
	v_pk_mul_f32 v[160:161], v[174:175], v[180:181]
	v_pk_mul_f32 v[172:173], v[172:173], v[182:183]
	v_pk_mul_f32 v[60:61], v[60:61], v[160:161]
	v_cvt_f32_ubyte0_e32 v161, v159
	v_pk_mul_f32 v[162:163], v[178:179], v[162:163]
	v_max_f32_e32 v161, 0.5, v161
	v_pk_mul_f32 v[64:65], v[64:65], v[172:173]
	v_pk_mul_f32 v[62:63], v[62:63], v[162:163]
	v_cvt_f32_ubyte0_e32 v160, v158
	v_rcp_f32_e32 v162, v161
	v_cvt_f32_ubyte1_e32 v161, v158
	v_cvt_f32_ubyte2_e32 v172, v158
	v_cvt_f32_ubyte2_e32 v173, v159
	v_cvt_f32_ubyte3_e32 v158, v158
	v_cvt_f32_ubyte1_e32 v163, v159
	v_max_f32_e32 v172, 0.5, v172
	v_max_f32_e32 v173, 0.5, v173
	v_max_f32_e32 v158, 0.5, v158
	v_max_f32_e32 v163, 0.5, v163
	v_rcp_f32_e32 v172, v172
	v_rcp_f32_e32 v174, v173
	v_rcp_f32_e32 v173, v158
	v_rcp_f32_e32 v163, v163
	v_pk_mul_f32 v[66:67], v[66:67], v[176:177]
	v_cvt_f32_ubyte3_e32 v177, v154
	v_cvt_f32_ubyte2_e32 v176, v154
	v_cvt_f32_ubyte1_e32 v179, v154
	v_cvt_f32_ubyte0_e32 v178, v154
	v_cvt_f32_ubyte3_e32 v154, v159
	v_pk_mul_f32 v[172:173], v[172:173], v[176:177]
	v_max_f32_e32 v154, 0.5, v154
	v_cvt_f32_ubyte1_e32 v177, v155
	v_cvt_f32_ubyte0_e32 v176, v155
	v_max_f32_e32 v160, 0.5, v160
	v_max_f32_e32 v161, 0.5, v161
	v_rcp_f32_e32 v175, v154
	v_cvt_f32_ubyte3_e32 v159, v155
	v_cvt_f32_ubyte2_e32 v158, v155
	v_pk_mul_f32 v[154:155], v[162:163], v[176:177]
	v_rcp_f32_e32 v160, v160
	v_rcp_f32_e32 v161, v161
	v_pk_mul_f32 v[52:53], v[52:53], v[154:155]
	v_add_u32_e32 v154, s70, v1
	v_ashrrev_i32_e32 v155, 31, v154
	v_lshlrev_b64 v[154:155], 12, v[154:155]
	v_pk_mul_f32 v[158:159], v[174:175], v[158:159]
	v_lshl_add_u64 v[154:155], s[46:47], 0, v[154:155]
	v_pk_mul_f32 v[160:161], v[160:161], v[178:179]
	v_pk_mul_f32 v[54:55], v[54:55], v[158:159]
	v_lshl_add_u64 v[158:159], v[154:155], 0, v[2:3]
	v_pk_mul_f32 v[56:57], v[56:57], v[160:161]
	s_nop 0
	v_pk_mul_f32 v[58:59], v[58:59], v[172:173]
	v_cvt_f32_ubyte0_e32 v173, v171
	v_max_f32_e32 v173, 0.5, v173
	v_cvt_f32_ubyte0_e32 v172, v170
	v_rcp_f32_e32 v174, v173
	v_cvt_f32_ubyte1_e32 v173, v170
	v_cvt_f32_ubyte2_e32 v176, v170
	v_cvt_f32_ubyte2_e32 v177, v171
	v_cvt_f32_ubyte3_e32 v170, v170
	v_cvt_f32_ubyte1_e32 v175, v171
	v_max_f32_e32 v176, 0.5, v176
	v_max_f32_e32 v177, 0.5, v177
	v_max_f32_e32 v170, 0.5, v170
	v_max_f32_e32 v175, 0.5, v175
	v_rcp_f32_e32 v176, v176
	v_rcp_f32_e32 v178, v177
	v_rcp_f32_e32 v177, v170
	v_rcp_f32_e32 v175, v175
	v_cvt_f32_ubyte3_e32 v181, v168
	v_cvt_f32_ubyte2_e32 v180, v168
	v_cvt_f32_ubyte1_e32 v183, v168
	v_cvt_f32_ubyte0_e32 v182, v168
	v_cvt_f32_ubyte3_e32 v168, v171
	v_max_f32_e32 v172, 0.5, v172
	v_max_f32_e32 v173, 0.5, v173
	v_max_f32_e32 v168, 0.5, v168
	v_rcp_f32_e32 v172, v172
	v_rcp_f32_e32 v173, v173
	v_rcp_f32_e32 v179, v168
	v_pk_mul_f32 v[176:177], v[176:177], v[180:181]
	v_cvt_f32_ubyte1_e32 v181, v169
	v_cvt_f32_ubyte0_e32 v180, v169
	v_cvt_f32_ubyte3_e32 v171, v169
	v_cvt_f32_ubyte2_e32 v170, v169
	v_pk_mul_f32 v[168:169], v[174:175], v[180:181]
	v_pk_mul_f32 v[172:173], v[172:173], v[182:183]
	v_pk_mul_f32 v[44:45], v[44:45], v[168:169]
	v_cvt_f32_ubyte0_e32 v169, v157
	v_pk_mul_f32 v[170:171], v[178:179], v[170:171]
	v_max_f32_e32 v169, 0.5, v169
	v_pk_mul_f32 v[48:49], v[48:49], v[172:173]
	v_pk_mul_f32 v[46:47], v[46:47], v[170:171]
	v_cvt_f32_ubyte0_e32 v168, v156
	v_rcp_f32_e32 v170, v169
	v_cvt_f32_ubyte1_e32 v169, v156
	v_cvt_f32_ubyte2_e32 v172, v156
	v_cvt_f32_ubyte2_e32 v173, v157
	v_cvt_f32_ubyte3_e32 v156, v156
	v_cvt_f32_ubyte1_e32 v171, v157
	v_max_f32_e32 v172, 0.5, v172
	v_max_f32_e32 v173, 0.5, v173
	v_max_f32_e32 v156, 0.5, v156
	v_max_f32_e32 v171, 0.5, v171
	v_rcp_f32_e32 v172, v172
	v_rcp_f32_e32 v174, v173
	v_rcp_f32_e32 v173, v156
	v_rcp_f32_e32 v171, v171
	v_pk_mul_f32 v[50:51], v[50:51], v[176:177]
	v_cvt_f32_ubyte3_e32 v177, v152
	v_cvt_f32_ubyte2_e32 v176, v152
	v_cvt_f32_ubyte1_e32 v179, v152
	v_cvt_f32_ubyte0_e32 v178, v152
	v_cvt_f32_ubyte3_e32 v152, v157
	v_pk_mul_f32 v[172:173], v[172:173], v[176:177]
	v_max_f32_e32 v152, 0.5, v152
	v_cvt_f32_ubyte1_e32 v177, v153
	v_cvt_f32_ubyte0_e32 v176, v153
	v_max_f32_e32 v168, 0.5, v168
	v_max_f32_e32 v169, 0.5, v169
	v_rcp_f32_e32 v175, v152
	v_cvt_f32_ubyte3_e32 v157, v153
	v_cvt_f32_ubyte2_e32 v156, v153
	v_pk_mul_f32 v[152:153], v[170:171], v[176:177]
	v_rcp_f32_e32 v168, v168
	v_rcp_f32_e32 v169, v169
	v_pk_mul_f32 v[36:37], v[36:37], v[152:153]
	v_add_u32_e32 v152, s71, v1
	v_ashrrev_i32_e32 v153, 31, v152
	v_lshlrev_b64 v[152:153], 12, v[152:153]
	v_lshl_add_u64 v[152:153], s[46:47], 0, v[152:153]
	v_pk_mul_f32 v[168:169], v[168:169], v[178:179]
	v_pk_mul_f32 v[156:157], v[174:175], v[156:157]
	v_lshl_add_u64 v[152:153], v[152:153], 0, v[2:3]
	v_pk_mul_f32 v[40:41], v[40:41], v[168:169]
	v_pk_mul_f32 v[38:39], v[38:39], v[156:157]
	s_nop 0
	s_waitcnt vmcnt(0)
;     __device__ __forceinline__ void mid(f32x4 (&acc)[2][2][4][2], const Unit& u, int wr, int wc, int fr, int fq) const {
;     ...
;         for (int g = 0; g < 8; ++g) {
;             const int ai = g >> 2, m = g & 3;
;             if (g < 7) {
; #pragma unroll
;                 for (int bj = 0; bj < 2; ++bj) { const unsigned char* p = gates + (size_t)ROW_OF((g + 1) >> 2, (g + 1) & 3) * (2 * D) + col0 + bj * 128; an[bj] = *(const u32x2*)p; bn[bj] = *(const u32x2*)(p + D); }
;             }
; #pragma unroll
;             for (int bj = 0; bj < 2; ++bj) {
;                 const unsigned a0 = ac[bj].x, a1 = ac[bj].y, b0 = bc[bj].x, b1 = bc[bj].y;
;                 f32x4 r0, r1;
; #pragma unroll
;                 for (int j = 0; j < 4; ++j) {
;                     r0[j] = (float)((a0 >> (8 * j)) & 0xff) * __builtin_amdgcn_rcpf(fmaxf((float)((b0 >> (8 * j)) & 0xff), 0.5f));
;                     r1[j] = (float)((a1 >> (8 * j)) & 0xff) * __builtin_amdgcn_rcpf(fmaxf((float)((b1 >> (8 * j)) & 0xff), 0.5f));
;                 }
;                 acc[ai][bj][m][0] = acc[ai][bj][m][0] * r0; acc[ai][bj][m][1] = acc[ai][bj][m][1] * r1;
;             }
;             if (g < 7) { ac[0] = an[0]; ac[1] = an[1]; bc[0] = bn[0]; bc[1] = bn[1]; }
	v_mov_b64_e32 v[160:161], v[220:221]
	v_mov_b64_e32 v[162:163], v[222:223]
	v_mov_b64_e32 v[154:155], v[224:225]
	v_mov_b64_e32 v[158:159], v[226:227]
	v_mov_b64_e32 v[156:157], v[228:229]
	v_mov_b64_e32 v[168:169], v[230:231]
	v_mov_b64_e32 v[2:3], v[232:233]
	v_mov_b64_e32 v[152:153], v[234:235]
	v_cvt_f32_ubyte0_e32 v1, v162
	v_max_f32_e32 v1, 0.5, v1
	v_rcp_f32_e32 v170, v1
	v_cvt_f32_ubyte0_e32 v1, v163
	v_max_f32_e32 v1, 0.5, v1
	v_pk_mul_f32 v[42:43], v[42:43], v[172:173]
	v_rcp_f32_e32 v172, v1
	v_cvt_f32_ubyte1_e32 v1, v162
	v_max_f32_e32 v1, 0.5, v1
	v_rcp_f32_e32 v171, v1
	v_cvt_f32_ubyte1_e32 v1, v163
	v_max_f32_e32 v1, 0.5, v1
	v_rcp_f32_e32 v173, v1
	v_cvt_f32_ubyte2_e32 v1, v162
	v_max_f32_e32 v1, 0.5, v1
	v_rcp_f32_e32 v174, v1
	v_cvt_f32_ubyte2_e32 v1, v163
	v_max_f32_e32 v1, 0.5, v1
	v_rcp_f32_e32 v176, v1
	v_cvt_f32_ubyte3_e32 v1, v162
	v_max_f32_e32 v1, 0.5, v1
	v_rcp_f32_e32 v175, v1
	v_cvt_f32_ubyte3_e32 v1, v163
	v_max_f32_e32 v1, 0.5, v1
	v_cvt_f32_ubyte3_e32 v179, v160
	v_cvt_f32_ubyte2_e32 v178, v160
	v_rcp_f32_e32 v177, v1
	v_pk_mul_f32 v[174:175], v[174:175], v[178:179]
	v_cvt_f32_ubyte1_e32 v179, v161
	v_cvt_f32_ubyte0_e32 v178, v161
	v_cvt_f32_ubyte0_e32 v1, v158
	v_cvt_f32_ubyte1_e32 v181, v160
	v_cvt_f32_ubyte0_e32 v180, v160
	v_cvt_f32_ubyte3_e32 v163, v161
	v_cvt_f32_ubyte2_e32 v162, v161
	v_pk_mul_f32 v[160:161], v[172:173], v[178:179]
	v_max_f32_e32 v1, 0.5, v1
	v_pk_mul_f32 v[28:29], v[28:29], v[160:161]
	v_rcp_f32_e32 v160, v1
	v_cvt_f32_ubyte0_e32 v1, v159
	v_pk_mul_f32 v[162:163], v[176:177], v[162:163]
	v_max_f32_e32 v1, 0.5, v1
	v_pk_mul_f32 v[30:31], v[30:31], v[162:163]
	v_rcp_f32_e32 v162, v1
	v_cvt_f32_ubyte1_e32 v1, v158
	v_max_f32_e32 v1, 0.5, v1
	v_rcp_f32_e32 v161, v1
	v_cvt_f32_ubyte1_e32 v1, v159
	v_max_f32_e32 v1, 0.5, v1
	v_rcp_f32_e32 v163, v1
	v_cvt_f32_ubyte2_e32 v1, v158
	v_pk_mul_f32 v[170:171], v[170:171], v[180:181]
	v_max_f32_e32 v1, 0.5, v1
	v_pk_mul_f32 v[32:33], v[32:33], v[170:171]
	v_rcp_f32_e32 v170, v1
	v_cvt_f32_ubyte2_e32 v1, v159
	v_max_f32_e32 v1, 0.5, v1
	v_rcp_f32_e32 v172, v1
	v_cvt_f32_ubyte3_e32 v1, v158
	v_max_f32_e32 v1, 0.5, v1
	v_rcp_f32_e32 v171, v1
	v_cvt_f32_ubyte3_e32 v1, v159
	v_max_f32_e32 v1, 0.5, v1
	v_pk_mul_f32 v[34:35], v[34:35], v[174:175]
	v_cvt_f32_ubyte3_e32 v175, v154
	v_cvt_f32_ubyte2_e32 v174, v154
	v_rcp_f32_e32 v173, v1
	v_pk_mul_f32 v[170:171], v[170:171], v[174:175]
	v_cvt_f32_ubyte1_e32 v175, v155
	v_cvt_f32_ubyte0_e32 v174, v155
	v_cvt_f32_ubyte1_e32 v177, v154
	v_cvt_f32_ubyte0_e32 v176, v154
	v_cvt_f32_ubyte3_e32 v159, v155
	v_cvt_f32_ubyte2_e32 v158, v155
	v_pk_mul_f32 v[154:155], v[162:163], v[174:175]
	v_pk_mul_f32 v[158:159], v[172:173], v[158:159]
	v_pk_mul_f32 v[20:21], v[20:21], v[154:155]
	v_cvt_f32_ubyte0_e32 v1, v168
	v_max_f32_e32 v1, 0.5, v1
	v_rcp_f32_e32 v154, v1
	v_cvt_f32_ubyte0_e32 v1, v169
	v_max_f32_e32 v1, 0.5, v1
	v_pk_mul_f32 v[22:23], v[22:23], v[158:159]
	v_rcp_f32_e32 v158, v1
	v_cvt_f32_ubyte1_e32 v1, v168
	v_max_f32_e32 v1, 0.5, v1
	v_rcp_f32_e32 v155, v1
	v_cvt_f32_ubyte1_e32 v1, v169
	v_max_f32_e32 v1, 0.5, v1
	v_rcp_f32_e32 v159, v1
	v_cvt_f32_ubyte2_e32 v1, v168
	v_pk_mul_f32 v[160:161], v[160:161], v[176:177]
	v_max_f32_e32 v1, 0.5, v1
	v_pk_mul_f32 v[24:25], v[24:25], v[160:161]
	v_rcp_f32_e32 v160, v1
	v_cvt_f32_ubyte2_e32 v1, v169
	v_max_f32_e32 v1, 0.5, v1
	v_rcp_f32_e32 v162, v1
	v_cvt_f32_ubyte3_e32 v1, v168
	v_max_f32_e32 v1, 0.5, v1
	v_rcp_f32_e32 v161, v1
	v_cvt_f32_ubyte3_e32 v1, v169
	v_max_f32_e32 v1, 0.5, v1
	v_cvt_f32_ubyte1_e32 v173, v156
	v_cvt_f32_ubyte0_e32 v172, v156
	v_rcp_f32_e32 v163, v1
	v_cvt_f32_ubyte0_e32 v1, v152
	v_pk_mul_f32 v[26:27], v[26:27], v[170:171]
	v_cvt_f32_ubyte3_e32 v171, v156
	v_cvt_f32_ubyte2_e32 v170, v156
	v_pk_mul_f32 v[154:155], v[154:155], v[172:173]
	v_max_f32_e32 v1, 0.5, v1
	v_pk_mul_f32 v[160:161], v[160:161], v[170:171]
	v_cvt_f32_ubyte1_e32 v171, v157
	v_cvt_f32_ubyte0_e32 v170, v157
	v_pk_mul_f32 v[16:17], v[16:17], v[154:155]
	v_rcp_f32_e32 v154, v1
	v_cvt_f32_ubyte0_e32 v1, v153
	v_cvt_f32_ubyte3_e32 v169, v157
	v_cvt_f32_ubyte2_e32 v168, v157
	v_pk_mul_f32 v[156:157], v[158:159], v[170:171]
	v_max_f32_e32 v1, 0.5, v1
	v_pk_mul_f32 v[12:13], v[12:13], v[156:157]
	v_rcp_f32_e32 v156, v1
	v_cvt_f32_ubyte1_e32 v1, v152
	v_max_f32_e32 v1, 0.5, v1
	v_rcp_f32_e32 v155, v1
	v_cvt_f32_ubyte1_e32 v1, v153
	v_max_f32_e32 v1, 0.5, v1
	v_rcp_f32_e32 v157, v1
	v_cvt_f32_ubyte2_e32 v1, v152
	v_pk_mul_f32 v[158:159], v[162:163], v[168:169]
	v_max_f32_e32 v1, 0.5, v1
	v_pk_mul_f32 v[14:15], v[14:15], v[158:159]
	v_rcp_f32_e32 v158, v1
	v_cvt_f32_ubyte2_e32 v1, v153
	v_max_f32_e32 v1, 0.5, v1
	v_pk_mul_f32 v[18:19], v[18:19], v[160:161]
	v_rcp_f32_e32 v160, v1
	v_cvt_f32_ubyte3_e32 v1, v152
	v_max_f32_e32 v1, 0.5, v1
	v_rcp_f32_e32 v159, v1
	v_cvt_f32_ubyte3_e32 v1, v153
	v_max_f32_e32 v1, 0.5, v1
	v_rcp_f32_e32 v161, v1
	v_cvt_f32_ubyte3_e32 v163, v2
	v_cvt_f32_ubyte2_e32 v162, v2
	v_cvt_f32_ubyte1_e32 v169, v2
	v_cvt_f32_ubyte0_e32 v168, v2
	v_pk_mul_f32 v[158:159], v[158:159], v[162:163]
	v_cvt_f32_ubyte3_e32 v153, v3
	v_cvt_f32_ubyte2_e32 v152, v3
	v_cvt_f32_ubyte1_e32 v163, v3
	v_cvt_f32_ubyte0_e32 v162, v3
	v_pk_mul_f32 v[154:155], v[154:155], v[168:169]
	v_pk_mul_f32 v[2:3], v[156:157], v[162:163]
	v_pk_mul_f32 v[152:153], v[160:161], v[152:153]
	v_pk_mul_f32 v[10:11], v[10:11], v[158:159]
	v_pk_mul_f32 v[8:9], v[8:9], v[154:155]
	v_pk_mul_f32 v[6:7], v[6:7], v[152:153]
	v_pk_mul_f32 v[4:5], v[4:5], v[2:3]
	s_branch .LBB0_752
